# x->bf16 prologue loop: all 8 row loads issued up front with counted vmcnt(7) instead of load/vmcnt(0)/store per chunk; plus pool rewrite
# speedup vs baseline: 1.0229x; 1.0128x over previous
.LBB0_11:
	v_lshl_add_u64 v[26:27], s[52:53], 0, v[8:9]
	v_add_co_u32_e64 v54, s[4:5], s21, v26
	s_nop 1
	v_addc_co_u32_e64 v55, s[4:5], 0, v27, s[4:5]
	s_waitcnt lgkmcnt(0)
	global_load_dwordx4 v[22:25], v[6:7], off offset:-4096 nt
	global_load_dwordx4 v[26:29], v[6:7], off offset:-3072 nt
	global_load_dwordx4 v[30:33], v[6:7], off offset:-2048 nt
	global_load_dwordx4 v[34:37], v[6:7], off offset:-1024 nt
	global_load_dwordx4 v[38:41], v[6:7], off nt
	global_load_dwordx4 v[42:45], v[6:7], off offset:1024 nt
	global_load_dwordx4 v[46:49], v[6:7], off offset:2048 nt
	global_load_dwordx4 v[50:53], v[6:7], off offset:3072 nt
	v_cmp_lt_i32_e64 s[4:5], v14, v13
	s_nop 1
	v_cndmask_b32_e64 v21, v3, v14, s[4:5]
	s_waitcnt vmcnt(7)
	v_mul_f32_e32 v56, v23, v23
	v_mul_f32_e32 v57, v25, v25
	v_fmac_f32_e32 v56, v22, v22
	v_fmac_f32_e32 v57, v24, v24
	v_add_f32_e32 v58, v56, v57
	v_cvt_pk_bf16_f32 v22, v22, v23
	v_cvt_pk_bf16_f32 v23, v24, v25
	global_store_dwordx2 v[54:55], v[22:23], off
	s_waitcnt vmcnt(7)
	v_mul_f32_e32 v56, v27, v27
	v_mul_f32_e32 v57, v29, v29
	v_fmac_f32_e32 v56, v26, v26
	v_fmac_f32_e32 v57, v28, v28
	v_add_f32_e32 v56, v56, v57
	v_add_f32_e32 v58, v58, v56
	v_cvt_pk_bf16_f32 v26, v26, v27
	v_cvt_pk_bf16_f32 v27, v28, v29
	global_store_dwordx2 v[54:55], v[26:27], off offset:512
	s_waitcnt vmcnt(7)
	v_mul_f32_e32 v56, v31, v31
	v_mul_f32_e32 v57, v33, v33
	v_fmac_f32_e32 v56, v30, v30
	v_fmac_f32_e32 v57, v32, v32
	v_add_f32_e32 v56, v56, v57
	v_add_f32_e32 v58, v58, v56
	v_cvt_pk_bf16_f32 v30, v30, v31
	v_cvt_pk_bf16_f32 v31, v32, v33
	global_store_dwordx2 v[54:55], v[30:31], off offset:1024
	s_waitcnt vmcnt(7)
	v_mul_f32_e32 v56, v35, v35
	v_mul_f32_e32 v57, v37, v37
	v_fmac_f32_e32 v56, v34, v34
	v_fmac_f32_e32 v57, v36, v36
	v_add_f32_e32 v56, v56, v57
	v_add_f32_e32 v58, v58, v56
	v_cvt_pk_bf16_f32 v34, v34, v35
	v_cvt_pk_bf16_f32 v35, v36, v37
	global_store_dwordx2 v[54:55], v[34:35], off offset:1536
	s_waitcnt vmcnt(7)
	v_mul_f32_e32 v56, v39, v39
	v_mul_f32_e32 v57, v41, v41
	v_fmac_f32_e32 v56, v38, v38
	v_fmac_f32_e32 v57, v40, v40
	v_add_f32_e32 v56, v56, v57
	v_add_f32_e32 v58, v58, v56
	v_cvt_pk_bf16_f32 v38, v38, v39
	v_cvt_pk_bf16_f32 v39, v40, v41
	global_store_dwordx2 v[54:55], v[38:39], off offset:2048
	s_waitcnt vmcnt(7)
	v_mul_f32_e32 v56, v43, v43
	v_mul_f32_e32 v57, v45, v45
	v_fmac_f32_e32 v56, v42, v42
	v_fmac_f32_e32 v57, v44, v44
	v_add_f32_e32 v56, v56, v57
	v_add_f32_e32 v58, v58, v56
	v_cvt_pk_bf16_f32 v42, v42, v43
	v_cvt_pk_bf16_f32 v43, v44, v45
	global_store_dwordx2 v[54:55], v[42:43], off offset:2560
	s_waitcnt vmcnt(7)
	v_mul_f32_e32 v56, v47, v47
	v_mul_f32_e32 v57, v49, v49
	v_fmac_f32_e32 v56, v46, v46
	v_fmac_f32_e32 v57, v48, v48
	v_add_f32_e32 v56, v56, v57
	v_add_f32_e32 v58, v58, v56
	v_cvt_pk_bf16_f32 v46, v46, v47
	v_cvt_pk_bf16_f32 v47, v48, v49
	global_store_dwordx2 v[54:55], v[46:47], off offset:3072
	s_waitcnt vmcnt(7)
	v_mul_f32_e32 v56, v51, v51
	v_mul_f32_e32 v57, v53, v53
	v_fmac_f32_e32 v56, v50, v50
	v_fmac_f32_e32 v57, v52, v52
	v_add_f32_e32 v56, v56, v57
	v_add_f32_e32 v58, v58, v56
	v_cvt_pk_bf16_f32 v50, v50, v51
	v_cvt_pk_bf16_f32 v51, v52, v53
	global_store_dwordx2 v[54:55], v[50:51], off offset:3584
	v_lshlrev_b32_e32 v21, 2, v21
	v_mov_b32_e32 v22, v58
	ds_bpermute_b32 v21, v21, v22
	v_cmp_lt_i32_e64 s[4:5], v15, v13
	s_waitcnt lgkmcnt(0)
	v_add_f32_e32 v21, v22, v21
	v_cndmask_b32_e64 v23, v3, v15, s[4:5]
	v_lshlrev_b32_e32 v23, 2, v23
	ds_bpermute_b32 v22, v23, v21
	v_cmp_lt_i32_e64 s[4:5], v16, v13
	s_waitcnt lgkmcnt(0)
	v_add_f32_e32 v21, v21, v22
	v_cndmask_b32_e64 v23, v3, v16, s[4:5]
	v_lshlrev_b32_e32 v23, 2, v23
	ds_bpermute_b32 v22, v23, v21
	v_cmp_lt_i32_e64 s[4:5], v17, v13
	s_waitcnt lgkmcnt(0)
	v_add_f32_e32 v21, v21, v22
	v_cndmask_b32_e64 v23, v3, v17, s[4:5]
	v_lshlrev_b32_e32 v23, 2, v23
	ds_bpermute_b32 v22, v23, v21
	v_cmp_lt_i32_e64 s[4:5], v18, v13
	s_waitcnt lgkmcnt(0)
	v_add_f32_e32 v21, v21, v22
	v_cndmask_b32_e64 v23, v3, v18, s[4:5]
	v_lshlrev_b32_e32 v23, 2, v23
	ds_bpermute_b32 v22, v23, v21
	v_cmp_lt_i32_e64 s[4:5], v19, v13
	s_waitcnt lgkmcnt(0)
	v_add_f32_e32 v21, v21, v22
	v_cndmask_b32_e64 v23, v3, v19, s[4:5]
	v_lshlrev_b32_e32 v22, 2, v23
	ds_bpermute_b32 v22, v22, v21
	s_and_saveexec_b64 s[4:5], vcc
	s_cbranch_execz .LBB0_10
	v_lshl_add_u64 v[24:25], s[52:53], 0, v[4:5]
	s_waitcnt lgkmcnt(0)
	v_add_f32_e32 v21, v21, v22
	global_store_dword v[24:25], v21, off
	s_branch .LBB0_10
